# combo28 + dn_prep: odd workgroups without a sample item start about 4 us later (three staggered groups instead of two)
# speedup vs baseline: 1.0080x; 1.0080x over previous
; __device__ __forceinline__ void dn_prep(const Params& p, LAS unsigned char* lds) {
;     const int tid = threadIdx.x, lane = tid & 63, wid = tid >> 6, fr = lane & 15, fq = lane >> 4;
;     LAS bf16_t* Qs = (LAS bf16_t*)(lds + L_QS); LAS bf16_t* Ks = (LAS bf16_t*)(lds + L_KS); LAS bf16_t* Kts = (LAS bf16_t*)(lds + L_KT); LAS bf16_t* Vts = (LAS bf16_t*)(lds + L_VT);
;     LAS float* As = (LAS float*)(lds + L_AS); LAS bf16_t* Tu = (LAS bf16_t*)(lds + L_TU); LAS bf16_t* Tw = (LAS bf16_t*)(lds + L_TW);
;     LAS float* beta_s = (LAS float*)(lds + L_BG); LAS float* G_s = beta_s + 64;
;     const bf16_t* Z = (const bf16_t*)(p.ws + WS_Z);
;     const float* BA = (const float*)(p.ws + WS_BA);
;     unsigned char* dn = (unsigned char*)p.out;
;     LAS float* cw_s = (LAS float*)(lds + 108032);
;     int hb = -1;
;     for (int ci = blockIdx.x; ci < NCH; ci += gridDim.x) {
;         const bool samp = ci >= 1024;
;         if ((ci & 3) != hb) { hb = ci & 3;
;             lds_barrier();
;             for (int idx = tid; idx < 1536; idx += 512) { const int j = idx / 384, r = idx - j * 384; cw_s[idx] = p.in[12][j * 1536 + (r >> 7) * 512 + hb * 128 + (r & 127)]; }
;             lds_barrier(); }
;         int b, n, h, chs, row0, ntok;
;         if (!samp) { h = ci & 3; n = (ci >> 2) & 31; b = ci >> 7; chs = ((b * 4 + h) << 5) + n; row0 = b * 2048 + n * 64; ntok = 64; }
;         else { const int s = ci - 1024; h = s & 3; b = s >> 2; n = 0; chs = 1024 + s; row0 = MP + b * 16; ntok = 16; }
;         bf16_t* gW = (bf16_t*)(dn + DN_W) + (size_t)chs * 8192; bf16_t* gQS = (bf16_t*)(dn + DN_QS) + (size_t)chs * 8192;
;         bf16_t* gKT = (bf16_t*)(dn + DN_KT) + (size_t)chs * 8192; bf16_t* gQK = (bf16_t*)(dn + DN_QK) + (size_t)chs * 4096;
;         bf16_t* gUT = (bf16_t*)(p.ws + WS_UT) + (size_t)chs * 8192; float* gG = (float*)(p.ws + WS_GB) + (size_t)chs * 64;
;         if (wid == 0) {
;             const bool valid = lane < ntok;
;             float be = 0.f, gl = 0.f;
;             if (valid) {
;                 const float bl = BA[(size_t)(row0 + lane) * 8 + h], al = BA[(size_t)(row0 + lane) * 8 + 4 + h] + p.in[14][h];
;                 be = __builtin_amdgcn_rcpf(1.0f + __expf(-bl));
;                 const float sp = al > 20.f ? al : log1pf(__expf(al));
;                 gl = -__expf(p.in[13][h]) * sp;
;             }
; #pragma unroll
.LBB0_187:
	s_cmp_lt_i32 s84, 3
	s_cselect_b64 s[4:5], -1, 0
	s_and_b64 s[0:1], s[4:5], s[2:3]
	s_andn2_b64 vcc, exec, s[0:1]
	s_cbranch_vccnz .LBB0_385
	s_cmpk_gt_i32 s33, 0x47f
	s_cbranch_scc1 .LBB0_385
	v_and_b32_e32 v152, 63, v184
	v_cmp_eq_u32_e32 vcc, 1, v152
	s_add_u32 s0, s50, 0xbc40000
	v_writelane_b32 v248, s4, 6
	v_cndmask_b32_e64 v160, 0, 1.0, vcc
	v_cmp_eq_u32_e32 vcc, 2, v152
	s_addc_u32 s1, s51, 0
	v_writelane_b32 v248, s5, 7
	v_cndmask_b32_e64 v161, 0, 1.0, vcc
	v_cmp_eq_u32_e32 vcc, 3, v152
	s_add_u32 s14, s48, 0x1200000
	v_writelane_b32 v248, s0, 8
	v_cndmask_b32_e64 v162, 0, 1.0, vcc
	v_cmp_eq_u32_e32 vcc, 4, v152
	s_addc_u32 s34, s49, 0
	v_writelane_b32 v248, s1, 9
	v_cndmask_b32_e64 v163, 0, 1.0, vcc
	v_cmp_eq_u32_e32 vcc, 5, v152
	s_add_u32 s0, s48, 0x2400000
	v_writelane_b32 v248, s0, 10
	v_cndmask_b32_e64 v164, 0, 1.0, vcc
	v_cmp_eq_u32_e32 vcc, 6, v152
	s_addc_u32 s0, s49, 0
	s_add_u32 s39, s48, 0x3600000
	v_cndmask_b32_e64 v165, 0, 1.0, vcc
	v_cmp_eq_u32_e32 vcc, 7, v152
	v_writelane_b32 v248, s0, 11
	s_addc_u32 s36, s49, 0
	v_cndmask_b32_e64 v166, 0, 1.0, vcc
	v_cmp_eq_u32_e32 vcc, 8, v152
	s_add_i32 s0, 0, 0x1a400
	v_lshlrev_b32_e32 v0, 2, v152
	v_cndmask_b32_e64 v167, 0, 1.0, vcc
	v_cmp_eq_u32_e32 vcc, 9, v152
	v_add_u32_e32 v153, s0, v0
	s_movk_i32 s0, 0xff
	v_cndmask_b32_e64 v168, 0, 1.0, vcc
	v_cmp_eq_u32_e32 vcc, 10, v152
	v_cmp_lt_u32_e64 s[4:5], s0, v184
	v_cmp_eq_u32_e64 s[0:1], 0, v152
	v_cndmask_b32_e64 v169, 0, 1.0, vcc
	v_cmp_eq_u32_e32 vcc, 11, v152
	v_writelane_b32 v248, s0, 12
	v_lshrrev_b32_e32 v1, 6, v184
	v_cndmask_b32_e64 v170, 0, 1.0, vcc
	v_cmp_eq_u32_e32 vcc, 12, v152
	v_writelane_b32 v248, s1, 13
	v_cndmask_b32_e64 v157, 0, 1.0, s[0:1]
	v_cndmask_b32_e64 v171, 0, 1.0, vcc
	v_cmp_eq_u32_e32 vcc, 13, v152
	v_cmp_gt_u32_e64 s[0:1], 2, v152
	v_bfe_u32 v3, v184, 6, 2
	v_cndmask_b32_e64 v172, 0, 1.0, vcc
	v_cmp_eq_u32_e32 vcc, 14, v152
	v_writelane_b32 v248, s0, 14
	v_lshlrev_b32_e32 v156, 4, v1
	v_cndmask_b32_e64 v173, 0, 1.0, vcc
	v_cmp_eq_u32_e32 vcc, 15, v152
	v_writelane_b32 v248, s1, 15
	v_cmp_gt_u32_e64 s[0:1], 4, v152
	v_cndmask_b32_e64 v174, 0, 1.0, vcc
	v_cmp_eq_u32_e32 vcc, 16, v152
	v_writelane_b32 v248, s0, 16
	v_lshlrev_b32_e32 v158, 3, v1
	v_cndmask_b32_e64 v175, 0, 1.0, vcc
	v_cmp_eq_u32_e32 vcc, 17, v152
	v_writelane_b32 v248, s1, 17
	v_cmp_gt_u32_e64 s[0:1], 8, v152
	v_cndmask_b32_e64 v176, 0, 1.0, vcc
	v_cmp_eq_u32_e32 vcc, 18, v152
	v_writelane_b32 v248, s0, 18
	v_lshlrev_b32_e32 v4, 10, v1
	v_cndmask_b32_e64 v177, 0, 1.0, vcc
	v_cmp_eq_u32_e32 vcc, 19, v152
	v_writelane_b32 v248, s1, 19
	v_cmp_gt_u32_e64 s[0:1], 16, v152
	v_cndmask_b32_e64 v178, 0, 1.0, vcc
	v_cmp_eq_u32_e32 vcc, 20, v152
	v_writelane_b32 v248, s0, 20
	v_lshrrev_b32_e32 v1, 1, v184
	v_cndmask_b32_e64 v179, 0, 1.0, vcc
	v_cmp_eq_u32_e32 vcc, 21, v152
	v_writelane_b32 v248, s1, 21
	v_cmp_gt_u32_e64 s[0:1], 32, v152
	v_cndmask_b32_e64 v180, 0, 1.0, vcc
	v_cmp_eq_u32_e32 vcc, 22, v152
	v_writelane_b32 v248, s0, 22
	v_and_b32_e32 v132, 0x1c0, v1
	v_cndmask_b32_e64 v181, 0, 1.0, vcc
	v_cmp_eq_u32_e32 vcc, 23, v152
	v_mov_b32_e32 v133, 0
	v_lshrrev_b32_e32 v1, 4, v184
	v_cndmask_b32_e64 v182, 0, 1.0, vcc
	v_cmp_eq_u32_e32 vcc, 24, v152
	v_writelane_b32 v248, s1, 23
	v_cmp_ne_u32_e64 s[0:1], 0, v3
	v_cndmask_b32_e64 v183, 0, 1.0, vcc
	v_cmp_eq_u32_e32 vcc, 25, v152
	s_add_i32 s37, 0, 0x1a500
	v_and_b32_e32 v2, 4, v1
	v_cndmask_b32_e64 v185, 0, 1.0, vcc
	v_cmp_eq_u32_e32 vcc, 26, v152
	v_writelane_b32 v248, s0, 24
	v_mov_b32_e32 v1, v133
	v_cndmask_b32_e64 v186, 0, 1.0, vcc
	v_cmp_eq_u32_e32 vcc, 27, v152
	v_add_u32_e32 v154, s37, v0
	v_writelane_b32 v248, s1, 25
	v_cndmask_b32_e64 v187, 0, 1.0, vcc
	v_cmp_eq_u32_e32 vcc, 28, v152
	v_lshl_add_u64 v[0:1], s[50:51], 0, v[0:1]
	s_mov_b64 s[0:1], 0xd0e8800
	v_cndmask_b32_e64 v188, 0, 1.0, vcc
	v_cmp_eq_u32_e32 vcc, 29, v152
	v_lshl_add_u64 v[136:137], v[0:1], 0, s[0:1]
	v_lshl_add_u32 v0, v184, 2, 0
	v_cndmask_b32_e64 v189, 0, 1.0, vcc
	v_cmp_eq_u32_e32 vcc, 30, v152
	v_add_u32_e32 v224, 0x1a600, v0
	s_add_u32 s31, s50, 0xbee8800
	v_cndmask_b32_e64 v190, 0, 1.0, vcc
	v_cmp_eq_u32_e32 vcc, 31, v152
	v_mbcnt_lo_u32_b32 v0, -1, 0
	v_cmp_gt_u32_e64 s[2:3], 64, v184
	v_cndmask_b32_e64 v191, 0, 1.0, vcc
	v_cmp_eq_u32_e32 vcc, 32, v152
	s_mov_b32 s41, 0
	v_lshlrev_b32_e32 v155, 4, v3
	v_cndmask_b32_e64 v192, 0, 1.0, vcc
	v_cmp_eq_u32_e32 vcc, 33, v152
	v_lshl_add_u64 v[134:135], s[48:49], 0, v[132:133]
	v_and_b32_e32 v159, 0x7f, v184
	v_cndmask_b32_e64 v193, 0, 1.0, vcc
	v_cmp_eq_u32_e32 vcc, 34, v152
	v_cmp_lt_u32_e64 s[20:21], 1, v3
	v_cmp_eq_u32_e64 s[22:23], 3, v3
	v_cndmask_b32_e64 v194, 0, 1.0, vcc
	v_cmp_eq_u32_e32 vcc, 35, v152
	s_addc_u32 s35, s51, 0
	s_mov_b32 s15, -1
	v_cndmask_b32_e64 v195, 0, 1.0, vcc
	v_cmp_eq_u32_e32 vcc, 36, v152
	v_mov_b32_e32 v225, 0x3ecc95a3
	s_movk_i32 s38, 0x1a00
	v_cndmask_b32_e64 v196, 0, 1.0, vcc
	v_cmp_eq_u32_e32 vcc, 37, v152
	s_mov_b64 s[42:43], 0x3000a00
	s_mov_b32 s8, 0x3000000
	v_cndmask_b32_e64 v197, 0, 1.0, vcc
	v_cmp_eq_u32_e32 vcc, 38, v152
	s_movk_i32 s9, 0x1800
	s_movk_i32 s10, 0x110
	v_cndmask_b32_e64 v198, 0, 1.0, vcc
	v_cmp_eq_u32_e32 vcc, 39, v152
	s_mov_b32 s11, 0x800000
	s_mov_b64 s[46:47], 0x3000e00
	v_cndmask_b32_e64 v199, 0, 1.0, vcc
	v_cmp_eq_u32_e32 vcc, 40, v152
	s_mov_b64 s[66:67], 0x3001200
	s_mov_b32 s12, 0x3001000
	v_cndmask_b32_e64 v200, 0, 1.0, vcc
	v_cmp_eq_u32_e32 vcc, 41, v152
	s_add_i32 s13, 0, 0x11800
	v_lshlrev_b32_e32 v226, 1, v4
	v_cndmask_b32_e64 v201, 0, 1.0, vcc
	v_cmp_eq_u32_e32 vcc, 42, v152
	v_lshlrev_b32_e32 v138, 1, v2
	v_mov_b32_e32 v140, 0x3f317218
	v_cndmask_b32_e64 v202, 0, 1.0, vcc
	v_cmp_eq_u32_e32 vcc, 43, v152
	v_mov_b32_e32 v227, 0x7f800000
	v_mov_b32_e32 v228, 0x7fc00000
	v_cndmask_b32_e64 v203, 0, 1.0, vcc
	v_cmp_eq_u32_e32 vcc, 44, v152
	v_mov_b32_e32 v229, 0xff800000
	v_mbcnt_hi_u32_b32 v230, -1, v0
	v_cndmask_b32_e64 v204, 0, 1.0, vcc
	v_cmp_eq_u32_e32 vcc, 45, v152
	s_mov_b32 s30, s33
	s_cmpk_lt_i32 s33, 0x80
	s_cbranch_scc0 .Ldn_ord3
	s_addk_i32 s30, 0x400
	s_branch .Ldn_ord0
.Ldn_ord3:
	s_bitcmp1_b32 s33, 0
	s_cbranch_scc0 .Ldn_ord0
	s_sleep 127
